# GroupNorm loop: the four per-token broadcast loads of the recurrence scale replaced by one load plus DPP quad broadcasts (fewer vector-memory lanes)
# speedup vs baseline: 1.0021x; 1.0021x over previous
; __device__ __forceinline__ f32x4 bf4(v2u u) { return (f32x4){bflo(u.x), bfhi(u.x), bflo(u.y), bfhi(u.y)}; }
; __device__ __forceinline__ void p3_gn_chunk(const Args& a, int ch, int lane) {
;     const int n = lane & 15, rg = lane >> 4, head = ch & 15, c0 = head * 64 + 4 * n; const int t0 = (ch >> 4) * 16 + 4 * rg;
;     const bf16* YR = (const bf16*)(a.ws + WS_YR); const bf16* ZB = (const bf16*)(a.ws + WS_ZB); bf16* Y = (bf16*)(a.ws + WS_XN); const float* RK = (const float*)(a.ws + WS_RK);
;     const f32x4 lw = ld4(a.in[16] + c0), lb = ld4(a.in[17] + c0);
;     f32x4 vimg[4];
; #pragma unroll
;     for (int cb = 0; cb < 4; ++cb) vimg[cb] = bf4(*(const v2u*)(a.ws + WS_VS + (size_t)ch * 2048 + cb * 512 + lane * 8));
; #pragma unroll
;     for (int e = 0; e < 4; ++e) { const int t = t0 + e;
;         f32x4 y = bf4(*(const v2u*)(YR + (size_t)t * 1024 + c0));
;         const f32x4 g = bf4(*(const v2u*)(ZB + (size_t)t * 5120 + 4096 + c0)); const float rk = RK[(size_t)t * 16 + head];
; __global__ void __launch_bounds__(NTHR, 2) hybrid_fwd(Args args) {
;     ...
;     for (int ch = F.gw; ch < (T / 16) * NH; ch += F.NGW) p3_gn_chunk(args, ch, F.lane);
.LBB0_640:
	s_lshl_b32 s100, s8, 11
	v_lshl_add_u64 v[128:129], s[100:101], 0, v[130:131]
	s_and_b32 s4, s8, 15
	s_and_b32 s5, s8, -16
	v_lshl_or_b32 v0, s4, 6, v30
	v_add_u32_e32 v26, s5, v31
	s_lshl_b32 s4, s4, 2
	v_lshlrev_b32_e32 v10, 1, v0
	v_ashrrev_i32_e32 v27, 31, v26
	v_mad_i64_i32 v[28:29], s[10:11], v26, s6, v[12:13]
	s_add_u32 s4, s2, s4
	v_or_b32_e32 v34, 1, v26
	v_or_b32_e32 v36, 2, v26
	v_or_b32_e32 v22, 3, v26
	v_lshl_add_u64 v[38:39], s[72:73], 0, v[10:11]
	v_lshlrev_b64 v[40:41], 11, v[26:27]
	v_lshl_add_u64 v[28:29], v[28:29], 0, v[10:11]
	v_lshlrev_b32_e32 v23, 2, v0
	s_addc_u32 s5, s3, 0
	v_lshlrev_b64 v[42:43], 6, v[26:27]
	v_mad_i64_i32 v[44:45], s[10:11], v34, s6, v[12:13]
	v_mad_i64_i32 v[46:47], s[10:11], v36, s6, v[12:13]
	v_mad_i64_i32 v[48:49], s[10:11], v22, s6, v[12:13]
	v_lshl_add_u64 v[40:41], v[38:39], 0, v[40:41]
	v_add_co_u32_e32 v28, vcc, s7, v28
	global_load_dwordx2 v[14:15], v[8:9], off
	global_load_dwordx2 v[16:17], v[8:9], off offset:512
	global_load_dwordx2 v[18:19], v[8:9], off offset:1024
	global_load_dwordx2 v[20:21], v[8:9], off offset:1536
	global_load_dwordx4 v[0:3], v23, s[12:13]
	global_load_dwordx4 v[4:7], v23, s[14:15]
	v_lshl_add_u64 v[24:25], s[60:61], 0, v[10:11]
	v_addc_co_u32_e32 v29, vcc, 0, v29, vcc
	v_lshl_add_u64 v[42:43], s[4:5], 0, v[42:43]
	v_lshl_add_u64 v[44:45], v[44:45], 0, v[10:11]
	v_lshl_add_u64 v[46:47], v[46:47], 0, v[10:11]
	v_lshl_add_u64 v[48:49], v[48:49], 0, v[10:11]
	global_load_dwordx2 v[120:121], v[128:129], off
	global_load_dwordx2 v[122:123], v[128:129], off offset:512
	global_load_dwordx2 v[124:125], v[128:129], off offset:1024
	global_load_dwordx2 v[126:127], v[128:129], off offset:1536
	s_nop 0
	global_load_dwordx2 v[60:61], v[28:29], off
	v_bfe_u32 v117, v30, 2, 2
	v_add_lshl_u32 v117, v26, v117, 6
	global_load_dword v133, v117, s[4:5]
	v_ashrrev_i32_e32 v35, 31, v34
	v_ashrrev_i32_e32 v37, 31, v36
	v_lshlrev_b64 v[50:51], 11, v[34:35]
	v_lshlrev_b64 v[52:53], 6, v[34:35]
	v_lshlrev_b64 v[54:55], 11, v[36:37]
	v_lshlrev_b64 v[56:57], 6, v[36:37]
	v_add_co_u32_e32 v42, vcc, s7, v44
	v_lshl_add_u64 v[28:29], v[38:39], 0, v[50:51]
	s_nop 0
	v_addc_co_u32_e32 v43, vcc, 0, v45, vcc
	v_lshl_add_u64 v[44:45], s[4:5], 0, v[52:53]
	v_lshl_add_u64 v[50:51], v[38:39], 0, v[54:55]
	v_lshl_add_u64 v[52:53], s[4:5], 0, v[56:57]
	v_lshlrev_b64 v[26:27], 12, v[26:27]
	v_lshl_add_u64 v[26:27], v[24:25], 0, v[26:27]
	v_lshlrev_b64 v[34:35], 12, v[34:35]
	v_lshl_add_u64 v[34:35], v[24:25], 0, v[34:35]
	v_add_co_u32_e32 v46, vcc, s7, v46
	v_ashrrev_i32_e32 v23, 31, v22
	s_nop 0
	v_addc_co_u32_e32 v47, vcc, 0, v47, vcc
	v_lshlrev_b64 v[58:59], 11, v[22:23]
	v_lshl_add_u64 v[38:39], v[38:39], 0, v[58:59]
	v_lshlrev_b64 v[36:37], 12, v[36:37]
	v_lshl_add_u64 v[36:37], v[24:25], 0, v[36:37]
	v_add_co_u32_e32 v48, vcc, s7, v48
	s_add_i32 s8, s8, s42
	s_nop 0
	v_addc_co_u32_e32 v49, vcc, 0, v49, vcc
	v_lshl_add_u64 v[8:9], v[8:9], 0, s[0:1]
	s_cmpk_gt_i32 s8, 0x3fff
	v_lshlrev_b64 v[118:119], 6, v[22:23]
	s_nop 0
	global_load_dwordx2 v[102:103], v[42:43], off
	s_nop 0
	v_lshl_add_u64 v[118:119], s[4:5], 0, v[118:119]
	s_nop 0
	global_load_dwordx2 v[108:109], v[46:47], off
	s_nop 0
	s_nop 0
	global_load_dwordx2 v[114:115], v[48:49], off
	s_nop 0
	s_waitcnt vmcnt(14)
	v_lshlrev_b32_e32 v54, 16, v14
	v_and_b32_e32 v56, 0xffff0000, v14
	s_waitcnt vmcnt(13)
	v_lshlrev_b32_e32 v55, 16, v16
	v_and_b32_e32 v57, 0xffff0000, v16
	s_waitcnt vmcnt(12)
	v_lshlrev_b32_e32 v62, 16, v18
	v_and_b32_e32 v64, 0xffff0000, v18
	s_waitcnt vmcnt(11)
	v_lshlrev_b32_e32 v63, 16, v20
	v_and_b32_e32 v65, 0xffff0000, v20
	v_lshlrev_b32_e32 v58, 16, v15
	v_lshlrev_b32_e32 v59, 16, v17
	s_waitcnt vmcnt(5)
	v_perm_b32 v40, v122, v120, s98
	v_perm_b32 v41, v126, v124, s98
	v_perm_b32 v100, v122, v120, s99
	v_perm_b32 v101, v126, v124, s99
	v_perm_b32 v106, v123, v121, s98
	v_perm_b32 v107, v127, v125, s98
	v_perm_b32 v112, v123, v121, s99
	v_perm_b32 v113, v127, v125, s99
	v_lshlrev_b32_e32 v69, 16, v41
	v_lshlrev_b32_e32 v68, 16, v40
	v_and_b32_e32 v41, 0xffff0000, v41
	v_and_b32_e32 v40, 0xffff0000, v40
	v_pk_add_f32 v[72:73], v[68:69], v[40:41]
	s_waitcnt vmcnt(4)
	v_lshlrev_b32_e32 v70, 16, v60
	v_add_f32_e32 v33, v72, v73
	v_mul_f32_e32 v14, 0xbfb8aa3b, v70
	v_exp_f32_e32 v14, v14
	v_add_f32_dpp v33, v33, v33 quad_perm:[1,0,3,2] row_mask:0xf bank_mask:0xf bound_ctrl:1
	v_and_b32_e32 v71, 0xffff0000, v60
	v_lshlrev_b32_e32 v60, 16, v61
	v_add_f32_dpp v33, v33, v33 quad_perm:[2,3,0,1] row_mask:0xf bank_mask:0xf bound_ctrl:1
	v_add_f32_e32 v14, 1.0, v14
	v_rcp_f32_e32 v72, v14
	v_add_f32_dpp v33, v33, v33 row_half_mirror row_mask:0xf bank_mask:0xf bound_ctrl:1
	v_and_b32_e32 v61, 0xffff0000, v61
	v_mul_f32_e32 v16, 0xbfb8aa3b, v71
	v_add_f32_dpp v33, v33, v33 row_mirror row_mask:0xf bank_mask:0xf bound_ctrl:1
	v_fmac_f32_e32 v40, 0xbc800000, v33
	v_fmac_f32_e32 v41, 0xbc800000, v33
	v_fmac_f32_e32 v69, 0xbc800000, v33
	v_fmac_f32_e32 v68, 0xbc800000, v33
	v_mov_b32_e32 v76, v69
	v_mov_b32_e32 v77, v41
	v_mov_b32_e32 v69, v40
	v_pk_mul_f32 v[40:41], v[76:77], v[76:77]
	v_pk_mul_f32 v[78:79], v[68:69], v[68:69]
	v_mul_f32_e32 v18, 0xbfb8aa3b, v60
	v_pk_mov_b32 v[80:81], v[78:79], v[40:41] op_sel:[1,0]
	v_mov_b32_e32 v79, v41
	v_pk_add_f32 v[40:41], v[80:81], v[78:79]
	v_mul_f32_e32 v20, 0xbfb8aa3b, v61
	v_add_f32_e32 v14, v40, v41
	v_exp_f32_e32 v16, v16
	v_exp_f32_e32 v18, v18
	v_add_f32_dpp v14, v14, v14 quad_perm:[1,0,3,2] row_mask:0xf bank_mask:0xf bound_ctrl:1
	v_exp_f32_e32 v20, v20
	v_add_f32_e32 v16, 1.0, v16
	v_add_f32_dpp v14, v14, v14 quad_perm:[2,3,0,1] row_mask:0xf bank_mask:0xf bound_ctrl:1
	v_add_f32_e32 v18, 1.0, v18
	v_add_f32_e32 v20, 1.0, v20
	v_add_f32_dpp v14, v14, v14 row_half_mirror row_mask:0xf bank_mask:0xf bound_ctrl:1
	v_rcp_f32_e32 v73, v16
	v_rcp_f32_e32 v74, v18
	v_add_f32_dpp v14, v14, v14 row_mirror row_mask:0xf bank_mask:0xf bound_ctrl:1
	v_fmamk_f32 v14, v14, 0x3c800000, v32
	v_rsq_f32_e32 v14, v14
	v_rcp_f32_e32 v75, v20
	v_pk_mul_f32 v[70:71], v[72:73], v[70:71]
	v_lshlrev_b32_e32 v66, 16, v19
	v_pk_mul_f32 v[40:41], v[76:77], v[14:15] op_sel_hi:[1,0]
	v_pk_mul_f32 v[68:69], v[68:69], v[14:15] op_sel_hi:[1,0]
	v_pk_fma_f32 v[40:41], v[2:3], v[40:41], v[6:7]
	v_pk_fma_f32 v[68:69], v[0:1], v[68:69], v[4:5]
	v_pk_mul_f32 v[60:61], v[74:75], v[60:61]
	s_waitcnt vmcnt(3)
; __device__ __forceinline__ f32x4 bf4(v2u u) { return (f32x4){bflo(u.x), bfhi(u.x), bflo(u.y), bfhi(u.y)}; }
; __device__ __forceinline__ v2u pk4(f32x4 v) { v2u o; o.x = pk2(v.x, v.y); o.y = pk2(v.z, v.w); return o; }
; __device__ __forceinline__ void p3_gn_chunk(const Args& a, int ch, int lane) {
;     ...
;     for (int e = 0; e < 4; ++e) { const int t = t0 + e;
;         f32x4 y = bf4(*(const v2u*)(YR + (size_t)t * 1024 + c0));
;         const f32x4 g = bf4(*(const v2u*)(ZB + (size_t)t * 5120 + 4096 + c0)); const float rk = RK[(size_t)t * 16 + head];
;         const float mean = row16_sum((y.x + y.y) + (y.z + y.w)) * (1.f / 64.f);
;         y = y - mean;
;         const float rstd = __builtin_amdgcn_rsqf(row16_sum((y.x * y.x + y.y * y.y) + (y.z * y.z + y.w * y.w)) * (1.f / 64.f) + GN_EPS);
;         const f32x4 v = {vimg[0][e], vimg[1][e], vimg[2][e], vimg[3][e]};
;         f32x4 o = y * rstd * lw + lb + v * rk;
; #pragma unroll
;         for (int k = 0; k < 4; ++k) o[k] *= g[k] * __builtin_amdgcn_rcpf(1.f + __expf(-g[k]));
;         *(v2u*)(Y + (size_t)t * 2048 + c0) = pk4(o); }
	v_mov_b32_dpp v10, v133 quad_perm:[0,0,0,0] row_mask:0xf bank_mask:0xf
	v_mov_b32_dpp v104, v133 quad_perm:[1,1,1,1] row_mask:0xf bank_mask:0xf
	v_mov_b32_dpp v110, v133 quad_perm:[2,2,2,2] row_mask:0xf bank_mask:0xf
	v_mov_b32_dpp v116, v133 quad_perm:[3,3,3,3] row_mask:0xf bank_mask:0xf
	s_nop 0
	v_pk_fma_f32 v[40:41], v[10:11], v[62:63], v[40:41] op_sel_hi:[0,1,1]
	v_pk_fma_f32 v[54:55], v[10:11], v[54:55], v[68:69] op_sel_hi:[0,1,1]
	v_pk_mul_f32 v[54:55], v[70:71], v[54:55]
	v_pk_mul_f32 v[40:41], v[60:61], v[40:41]
	v_cvt_pk_bf16_f32 v54, v54, v55
	v_cvt_pk_bf16_f32 v55, v40, v41
	global_store_dwordx2 v[26:27], v[54:55], off
	s_waitcnt vmcnt(1)
	v_mov_b32_e32 v26, v100
	v_mov_b32_e32 v27, v101
	v_mov_b32_e32 v28, v102
	v_mov_b32_e32 v29, v103
	v_mov_b32_e32 v10, v104
	s_nop 0
	v_lshlrev_b32_e32 v67, 16, v21
	s_nop 0
	v_lshlrev_b32_e32 v41, 16, v27
	v_lshlrev_b32_e32 v40, 16, v26
	v_and_b32_e32 v27, 0xffff0000, v27
	v_and_b32_e32 v26, 0xffff0000, v26
	v_pk_add_f32 v[44:45], v[40:41], v[26:27]
	s_nop 0
	v_lshlrev_b32_e32 v42, 16, v28
	v_add_f32_e32 v33, v44, v45
	v_mul_f32_e32 v14, 0xbfb8aa3b, v42
	v_exp_f32_e32 v14, v14
	v_add_f32_dpp v33, v33, v33 quad_perm:[1,0,3,2] row_mask:0xf bank_mask:0xf bound_ctrl:1
	v_and_b32_e32 v43, 0xffff0000, v28
	v_lshlrev_b32_e32 v28, 16, v29
	v_add_f32_dpp v33, v33, v33 quad_perm:[2,3,0,1] row_mask:0xf bank_mask:0xf bound_ctrl:1
	v_add_f32_e32 v14, 1.0, v14
	v_rcp_f32_e32 v44, v14
	v_add_f32_dpp v33, v33, v33 row_half_mirror row_mask:0xf bank_mask:0xf bound_ctrl:1
	v_and_b32_e32 v29, 0xffff0000, v29
	v_mul_f32_e32 v16, 0xbfb8aa3b, v43
	v_add_f32_dpp v33, v33, v33 row_mirror row_mask:0xf bank_mask:0xf bound_ctrl:1
	v_fmac_f32_e32 v26, 0xbc800000, v33
	v_fmac_f32_e32 v27, 0xbc800000, v33
	v_fmac_f32_e32 v41, 0xbc800000, v33
	v_fmac_f32_e32 v40, 0xbc800000, v33
	v_mov_b32_e32 v60, v41
	v_mov_b32_e32 v61, v27
	v_mov_b32_e32 v41, v26
	v_pk_mul_f32 v[26:27], v[60:61], v[60:61]
	v_pk_mul_f32 v[62:63], v[40:41], v[40:41]
	v_mul_f32_e32 v18, 0xbfb8aa3b, v28
	v_pk_mov_b32 v[68:69], v[62:63], v[26:27] op_sel:[1,0]
	v_mov_b32_e32 v63, v27
	v_pk_add_f32 v[26:27], v[68:69], v[62:63]
	v_mul_f32_e32 v20, 0xbfb8aa3b, v29
	v_add_f32_e32 v14, v26, v27
	v_exp_f32_e32 v16, v16
	v_exp_f32_e32 v18, v18
	v_add_f32_dpp v14, v14, v14 quad_perm:[1,0,3,2] row_mask:0xf bank_mask:0xf bound_ctrl:1
	v_exp_f32_e32 v20, v20
	v_add_f32_e32 v16, 1.0, v16
	v_add_f32_dpp v14, v14, v14 quad_perm:[2,3,0,1] row_mask:0xf bank_mask:0xf bound_ctrl:1
	v_add_f32_e32 v18, 1.0, v18
	v_add_f32_e32 v20, 1.0, v20
	v_add_f32_dpp v14, v14, v14 row_half_mirror row_mask:0xf bank_mask:0xf bound_ctrl:1
	v_rcp_f32_e32 v45, v16
	v_rcp_f32_e32 v54, v18
	v_add_f32_dpp v14, v14, v14 row_mirror row_mask:0xf bank_mask:0xf bound_ctrl:1
	v_fmamk_f32 v14, v14, 0x3c800000, v32
	v_rsq_f32_e32 v14, v14
	v_rcp_f32_e32 v55, v20
	v_pk_mul_f32 v[42:43], v[44:45], v[42:43]
	v_pk_mul_f32 v[26:27], v[60:61], v[14:15] op_sel_hi:[1,0]
	v_pk_mul_f32 v[40:41], v[40:41], v[14:15] op_sel_hi:[1,0]
	v_pk_fma_f32 v[26:27], v[2:3], v[26:27], v[6:7]
	v_pk_fma_f32 v[40:41], v[0:1], v[40:41], v[4:5]
	v_pk_mul_f32 v[28:29], v[54:55], v[28:29]
	s_nop 0
	v_pk_fma_f32 v[26:27], v[10:11], v[64:65], v[26:27] op_sel_hi:[0,1,1]
	v_pk_fma_f32 v[40:41], v[10:11], v[56:57], v[40:41] op_sel_hi:[0,1,1]
	v_pk_mul_f32 v[40:41], v[42:43], v[40:41]
	v_pk_mul_f32 v[26:27], v[28:29], v[26:27]
	v_cvt_pk_bf16_f32 v28, v40, v41
	v_cvt_pk_bf16_f32 v29, v26, v27
	global_store_dwordx2 v[34:35], v[28:29], off
	s_nop 0
	v_mov_b32_e32 v26, v106
	v_mov_b32_e32 v27, v107
	v_mov_b32_e32 v28, v108
	v_mov_b32_e32 v29, v109
	v_mov_b32_e32 v10, v110
	s_nop 0
	s_nop 0
	v_lshlrev_b32_e32 v35, 16, v27
	v_lshlrev_b32_e32 v34, 16, v26
	v_and_b32_e32 v27, 0xffff0000, v27
	v_and_b32_e32 v26, 0xffff0000, v26
	v_pk_add_f32 v[42:43], v[34:35], v[26:27]
	s_nop 0
	v_lshlrev_b32_e32 v40, 16, v28
	v_add_f32_e32 v33, v42, v43
	v_mul_f32_e32 v14, 0xbfb8aa3b, v40
	v_exp_f32_e32 v14, v14
	v_add_f32_dpp v33, v33, v33 quad_perm:[1,0,3,2] row_mask:0xf bank_mask:0xf bound_ctrl:1
	v_and_b32_e32 v41, 0xffff0000, v28
	v_lshlrev_b32_e32 v28, 16, v29
	v_add_f32_dpp v33, v33, v33 quad_perm:[2,3,0,1] row_mask:0xf bank_mask:0xf bound_ctrl:1
	v_add_f32_e32 v14, 1.0, v14
	v_rcp_f32_e32 v42, v14
	v_add_f32_dpp v33, v33, v33 row_half_mirror row_mask:0xf bank_mask:0xf bound_ctrl:1
	v_and_b32_e32 v29, 0xffff0000, v29
	v_mul_f32_e32 v16, 0xbfb8aa3b, v41
	v_add_f32_dpp v33, v33, v33 row_mirror row_mask:0xf bank_mask:0xf bound_ctrl:1
	v_fmac_f32_e32 v26, 0xbc800000, v33
	v_fmac_f32_e32 v27, 0xbc800000, v33
	v_fmac_f32_e32 v35, 0xbc800000, v33
	v_fmac_f32_e32 v34, 0xbc800000, v33
	v_mov_b32_e32 v46, v35
	v_mov_b32_e32 v47, v27
	v_mov_b32_e32 v35, v26
; __device__ __forceinline__ f32x4 bf4(v2u u) { return (f32x4){bflo(u.x), bfhi(u.x), bflo(u.y), bfhi(u.y)}; }
; __device__ __forceinline__ v2u pk4(f32x4 v) { v2u o; o.x = pk2(v.x, v.y); o.y = pk2(v.z, v.w); return o; }
; __device__ __forceinline__ void p3_gn_chunk(const Args& a, int ch, int lane) {
;     ...
;     for (int e = 0; e < 4; ++e) { const int t = t0 + e;
;         f32x4 y = bf4(*(const v2u*)(YR + (size_t)t * 1024 + c0));
;         const f32x4 g = bf4(*(const v2u*)(ZB + (size_t)t * 5120 + 4096 + c0)); const float rk = RK[(size_t)t * 16 + head];
;         const float mean = row16_sum((y.x + y.y) + (y.z + y.w)) * (1.f / 64.f);
;         y = y - mean;
;         const float rstd = __builtin_amdgcn_rsqf(row16_sum((y.x * y.x + y.y * y.y) + (y.z * y.z + y.w * y.w)) * (1.f / 64.f) + GN_EPS);
;         const f32x4 v = {vimg[0][e], vimg[1][e], vimg[2][e], vimg[3][e]};
;         f32x4 o = y * rstd * lw + lb + v * rk;
; #pragma unroll
;         for (int k = 0; k < 4; ++k) o[k] *= g[k] * __builtin_amdgcn_rcpf(1.f + __expf(-g[k]));
;         *(v2u*)(Y + (size_t)t * 2048 + c0) = pk4(o); }
	v_pk_mul_f32 v[26:27], v[46:47], v[46:47]
	v_pk_mul_f32 v[50:51], v[34:35], v[34:35]
	v_mul_f32_e32 v18, 0xbfb8aa3b, v28
	v_pk_mov_b32 v[52:53], v[50:51], v[26:27] op_sel:[1,0]
	v_mov_b32_e32 v51, v27
	v_pk_add_f32 v[26:27], v[52:53], v[50:51]
	v_mul_f32_e32 v20, 0xbfb8aa3b, v29
	v_add_f32_e32 v14, v26, v27
	v_exp_f32_e32 v16, v16
	v_exp_f32_e32 v18, v18
	v_add_f32_dpp v14, v14, v14 quad_perm:[1,0,3,2] row_mask:0xf bank_mask:0xf bound_ctrl:1
	v_exp_f32_e32 v20, v20
	v_add_f32_e32 v16, 1.0, v16
	v_add_f32_dpp v14, v14, v14 quad_perm:[2,3,0,1] row_mask:0xf bank_mask:0xf bound_ctrl:1
	v_add_f32_e32 v18, 1.0, v18
	v_add_f32_e32 v20, 1.0, v20
	v_add_f32_dpp v14, v14, v14 row_half_mirror row_mask:0xf bank_mask:0xf bound_ctrl:1
	v_rcp_f32_e32 v43, v16
	v_rcp_f32_e32 v44, v18
	v_add_f32_dpp v14, v14, v14 row_mirror row_mask:0xf bank_mask:0xf bound_ctrl:1
	v_fmamk_f32 v14, v14, 0x3c800000, v32
	v_rsq_f32_e32 v14, v14
	v_rcp_f32_e32 v45, v20
	v_pk_mul_f32 v[40:41], v[42:43], v[40:41]
	v_and_b32_e32 v16, 0xffff0000, v19
	v_pk_mul_f32 v[26:27], v[46:47], v[14:15] op_sel_hi:[1,0]
	v_pk_mul_f32 v[34:35], v[34:35], v[14:15] op_sel_hi:[1,0]
	v_pk_fma_f32 v[26:27], v[2:3], v[26:27], v[6:7]
	v_pk_fma_f32 v[34:35], v[0:1], v[34:35], v[4:5]
	v_pk_mul_f32 v[28:29], v[44:45], v[28:29]
	s_nop 0
	v_pk_fma_f32 v[26:27], v[10:11], v[66:67], v[26:27] op_sel_hi:[0,1,1]
	v_pk_fma_f32 v[34:35], v[10:11], v[58:59], v[34:35] op_sel_hi:[0,1,1]
	v_pk_mul_f32 v[34:35], v[40:41], v[34:35]
	v_pk_mul_f32 v[26:27], v[28:29], v[26:27]
	v_cvt_pk_bf16_f32 v28, v34, v35
	v_cvt_pk_bf16_f32 v29, v26, v27
	global_store_dwordx2 v[36:37], v[28:29], off
	s_nop 0
	v_mov_b32_e32 v26, v112
	v_mov_b32_e32 v27, v113
	v_mov_b32_e32 v28, v114
	v_mov_b32_e32 v29, v115
	v_mov_b32_e32 v10, v116
	s_nop 0
	v_lshlrev_b64 v[34:35], 6, v[22:23]
	v_lshl_add_u64 v[34:35], s[4:5], 0, v[34:35]
	v_lshlrev_b64 v[22:23], 12, v[22:23]
	v_and_b32_e32 v14, 0xffff0000, v15
	v_and_b32_e32 v15, 0xffff0000, v17
	v_and_b32_e32 v17, 0xffff0000, v21
	v_lshl_add_u64 v[22:23], v[24:25], 0, v[22:23]
	s_nop 0
	v_lshlrev_b32_e32 v19, 16, v27
	v_lshlrev_b32_e32 v18, 16, v26
	v_and_b32_e32 v21, 0xffff0000, v27
	v_and_b32_e32 v20, 0xffff0000, v26
	s_nop 0
	v_lshlrev_b32_e32 v24, 16, v28
	v_and_b32_e32 v25, 0xffff0000, v28
	v_lshlrev_b32_e32 v26, 16, v29
	v_and_b32_e32 v27, 0xffff0000, v29
	v_pk_add_f32 v[28:29], v[18:19], v[20:21]
	v_mul_f32_e32 v33, 0xbfb8aa3b, v24
	v_add_f32_e32 v28, v28, v29
	v_mul_f32_e32 v34, 0xbfb8aa3b, v25
	v_mul_f32_e32 v35, 0xbfb8aa3b, v26
	v_add_f32_dpp v28, v28, v28 quad_perm:[1,0,3,2] row_mask:0xf bank_mask:0xf bound_ctrl:1
	v_mul_f32_e32 v36, 0xbfb8aa3b, v27
	v_exp_f32_e32 v29, v33
	v_add_f32_dpp v28, v28, v28 quad_perm:[2,3,0,1] row_mask:0xf bank_mask:0xf bound_ctrl:1
	v_exp_f32_e32 v33, v34
	v_exp_f32_e32 v34, v35
	v_add_f32_dpp v28, v28, v28 row_half_mirror row_mask:0xf bank_mask:0xf bound_ctrl:1
	v_exp_f32_e32 v35, v36
	v_add_f32_e32 v29, 1.0, v29
	v_add_f32_dpp v28, v28, v28 row_mirror row_mask:0xf bank_mask:0xf bound_ctrl:1
	v_fmac_f32_e32 v20, 0xbc800000, v28
	v_fmac_f32_e32 v21, 0xbc800000, v28
	v_fmac_f32_e32 v19, 0xbc800000, v28
	v_fmac_f32_e32 v18, 0xbc800000, v28
	v_mov_b32_e32 v36, v19
	v_mov_b32_e32 v37, v21
	v_mov_b32_e32 v19, v20
	v_pk_mul_f32 v[20:21], v[36:37], v[36:37]
	v_pk_mul_f32 v[38:39], v[18:19], v[18:19]
	v_add_f32_e32 v33, 1.0, v33
	v_pk_mov_b32 v[40:41], v[38:39], v[20:21] op_sel:[1,0]
	v_mov_b32_e32 v39, v21
	v_pk_add_f32 v[20:21], v[40:41], v[38:39]
	v_rcp_f32_e32 v28, v29
	v_add_f32_e32 v20, v20, v21
	v_rcp_f32_e32 v29, v33
	v_add_f32_e32 v34, 1.0, v34
	v_add_f32_dpp v20, v20, v20 quad_perm:[1,0,3,2] row_mask:0xf bank_mask:0xf bound_ctrl:1
	v_add_f32_e32 v35, 1.0, v35
	v_rcp_f32_e32 v34, v34
	v_add_f32_dpp v20, v20, v20 quad_perm:[2,3,0,1] row_mask:0xf bank_mask:0xf bound_ctrl:1
	v_rcp_f32_e32 v35, v35
	v_pk_mul_f32 v[24:25], v[28:29], v[24:25]
	v_add_f32_dpp v20, v20, v20 row_half_mirror row_mask:0xf bank_mask:0xf bound_ctrl:1
	v_pk_mul_f32 v[26:27], v[34:35], v[26:27]
	s_nop 0
	v_add_f32_dpp v20, v20, v20 row_mirror row_mask:0xf bank_mask:0xf bound_ctrl:1
	v_fmamk_f32 v20, v20, 0x3c800000, v32
	v_rsq_f32_e32 v20, v20
	s_nop 0
	v_pk_mul_f32 v[28:29], v[36:37], v[20:21] op_sel_hi:[1,0]
	v_pk_mul_f32 v[18:19], v[18:19], v[20:21] op_sel_hi:[1,0]
	v_pk_fma_f32 v[2:3], v[2:3], v[28:29], v[6:7]
	v_pk_fma_f32 v[0:1], v[0:1], v[18:19], v[4:5]
	s_nop 0
	v_pk_fma_f32 v[2:3], v[10:11], v[16:17], v[2:3] op_sel_hi:[0,1,1]
	v_pk_fma_f32 v[0:1], v[10:11], v[14:15], v[0:1] op_sel_hi:[0,1,1]
	v_pk_mul_f32 v[0:1], v[24:25], v[0:1]
	v_pk_mul_f32 v[2:3], v[26:27], v[2:3]
	v_cvt_pk_bf16_f32 v0, v0, v1
	v_cvt_pk_bf16_f32 v1, v2, v3
	global_store_dwordx2 v[22:23], v[0:1], off
	s_cbranch_scc0 .LBB0_640
